# long conv L=4096 windows 0..9: K-chunk re-association (9 ds_read_b128 per 8 MFMA instead of 12), as already done for L=16384
# baseline (speedup 1.0000x reference)
; #define LDS_WAIT() asm volatile("s_waitcnt lgkmcnt(0)" ::: "memory")
; #define CONV_LD(A_, B0_, B1_, m_) do { const int xA_ = xw + 16 * (m_); A_ = *(const LAS bf16x8*)(fr + 2 * xA_ + ((xA_ >> LOGRS) << 4)); \
;             B0_ = *(const LAS bf16x8*)(ubp0 + 16 * (m_)); B1_ = *(const LAS bf16x8*)(ubp1 + 16 * (m_)); } while (0)
; #define CONV_KEEP(k_) asm volatile("" :: "v"(fa[k_][0]), "v"(fb0[k_][0]), "v"(fb1[k_][0]), "v"(fa[k_][1]), "v"(fb0[k_][1]), "v"(fb1[k_][1]))
; template <int L, int NB>
; DI void conv_unit(const Frame& F, int c, const bf16* FRg, const float* F0, const float* hyD, const bf16* UT, bf16* YT, int tok0, bool dry) {
;     ...
;         const int xw = xA0 + win * WSTEPS * 16;
;     ...
;         for (int m = 0; m < nst; ++m) { bf16x8 a_, b0_, b1_; CONV_LD(a_, b0_, b1_, m);
;             acc0 = __builtin_amdgcn_mfma_f32_32x32x16_bf16(a_, b0_, acc0, 0, 0, 0);
;             acc1 = __builtin_amdgcn_mfma_f32_32x32x16_bf16(a_, b1_, acc1, 0, 0, 0); }
;     ...
;         bf16x8 fa[3][2], fb0[3][2], fb1[3][2];
;         fa[2][0] = (bf16x8){0, 0, 0, 0, 0, 0, 0, 0}; fa[2][1] = fa[2][0]; fb0[2][0] = fa[2][0]; fb0[2][1] = fa[2][0]; fb1[2][0] = fa[2][0]; fb1[2][1] = fa[2][0];
;         CONV_GLD(0, 0); CONV_GLD(1, 1);
;         const int ng = nst >> 1;
;         int g = 0;
;         for (; g + 3 < ng; g += 3) {
;             CONV_MM(0); CONV_KEEP(2); CONV_GLD(2, g + 2);
;             CONV_MM(1); CONV_KEEP(0); CONV_GLD(0, g + 3);
;             CONV_MM(2); CONV_KEEP(1); CONV_GLD(1, g + 4);
;         }
;         CONV_MM(0); CONV_KEEP(2); CONV_GLD(2, g + 2);
;         CONV_MM(1); CONV_KEEP(0);
;         CONV_MM(2); CONV_KEEP(1);
;         CONV_KEEP(2);
;     ...
;         LDS_WAIT();
.LBB0_783:
	s_or_b64 exec, exec, s[38:39]
	v_and_b32_e32 v243, 31, v148
	v_lshlrev_b32_e32 v243, 7, v243
	v_sub_u32_e32 v240, 0xf80, v243
	v_lshrrev_b32_e32 v243, 5, v148
	v_lshl_add_u32 v240, v243, 5, v240
	v_add_u32_e32 v240, s1, v240
	v_mul_u32_u24_e32 v243, 0x260, v243
	v_sub_u32_e32 v238, v235, v243
	v_add_u32_e32 v239, 0x280, v238
	v_ashrrev_i32_e32 v241, 3, v240
	v_and_b32_e32 v241, -16, v241
	v_lshl_add_u32 v241, v240, 1, v241
	v_add_u32_e32 v243, 64, v240
	v_ashrrev_i32_e32 v242, 3, v243
	v_and_b32_e32 v242, -16, v242
	v_lshl_add_u32 v242, v243, 1, v242
	ds_read_b128 v[76:79], v241
	ds_read_b128 v[92:95], v238
	ds_read_b128 v[80:83], v241 offset:16
	ds_read_b128 v[96:99], v239
	ds_read_b128 v[84:87], v241 offset:32
	ds_read_b128 v[100:103], v238 offset:16
	ds_read_b128 v[88:91], v241 offset:48
	ds_read_b128 v[104:107], v239 offset:16
	ds_read_b128 v[108:111], v238 offset:32
	ds_read_b128 v[112:115], v242
	ds_read_b128 v[128:131], v238 offset:64
	ds_read_b128 v[116:119], v242 offset:16
	ds_read_b128 v[132:135], v239 offset:64
	ds_read_b128 v[120:123], v242 offset:32
	ds_read_b128 v[136:139], v238 offset:80
	ds_read_b128 v[124:127], v242 offset:48
	ds_read_b128 v[140:143], v239 offset:80
	ds_read_b128 v[144:147], v238 offset:96
	v_add_u32_e32 v243, 128, v240
	v_ashrrev_i32_e32 v241, 3, v243
	v_and_b32_e32 v241, -16, v241
	v_lshl_add_u32 v241, v243, 1, v241
	v_add_u32_e32 v243, 192, v240
	v_ashrrev_i32_e32 v242, 3, v243
	v_and_b32_e32 v242, -16, v242
	v_lshl_add_u32 v242, v243, 1, v242
	s_waitcnt lgkmcnt(9)
	v_mfma_f32_32x32x16_bf16 v[2:17], v[76:79], v[92:95], v[2:17]
	v_mfma_f32_32x32x16_bf16 v[18:33], v[76:79], v[96:99], v[18:33]
	ds_read_b128 v[76:79], v241
	ds_read_b128 v[92:95], v238 offset:128
	v_mfma_f32_32x32x16_bf16 v[2:17], v[80:83], v[96:99], v[2:17]
	v_mfma_f32_32x32x16_bf16 v[18:33], v[80:83], v[100:103], v[18:33]
	ds_read_b128 v[80:83], v241 offset:16
	ds_read_b128 v[96:99], v239 offset:128
	v_mfma_f32_32x32x16_bf16 v[2:17], v[84:87], v[100:103], v[2:17]
	v_mfma_f32_32x32x16_bf16 v[18:33], v[84:87], v[104:107], v[18:33]
	ds_read_b128 v[84:87], v241 offset:32
	ds_read_b128 v[100:103], v238 offset:144
	v_mfma_f32_32x32x16_bf16 v[2:17], v[88:91], v[104:107], v[2:17]
	v_mfma_f32_32x32x16_bf16 v[18:33], v[88:91], v[108:111], v[18:33]
	ds_read_b128 v[88:91], v241 offset:48
	ds_read_b128 v[104:107], v239 offset:144
	ds_read_b128 v[108:111], v238 offset:160
	s_waitcnt lgkmcnt(9)
	v_mfma_f32_32x32x16_bf16 v[2:17], v[112:115], v[128:131], v[2:17]
	v_mfma_f32_32x32x16_bf16 v[18:33], v[112:115], v[132:135], v[18:33]
	ds_read_b128 v[112:115], v242
	ds_read_b128 v[128:131], v238 offset:192
	v_mfma_f32_32x32x16_bf16 v[2:17], v[116:119], v[132:135], v[2:17]
	v_mfma_f32_32x32x16_bf16 v[18:33], v[116:119], v[136:139], v[18:33]
	ds_read_b128 v[116:119], v242 offset:16
	ds_read_b128 v[132:135], v239 offset:192
	v_mfma_f32_32x32x16_bf16 v[2:17], v[120:123], v[136:139], v[2:17]
	v_mfma_f32_32x32x16_bf16 v[18:33], v[120:123], v[140:143], v[18:33]
	ds_read_b128 v[120:123], v242 offset:32
	ds_read_b128 v[136:139], v238 offset:208
	v_mfma_f32_32x32x16_bf16 v[2:17], v[124:127], v[140:143], v[2:17]
	v_mfma_f32_32x32x16_bf16 v[18:33], v[124:127], v[144:147], v[18:33]
	ds_read_b128 v[124:127], v242 offset:48
	ds_read_b128 v[140:143], v239 offset:208
	ds_read_b128 v[144:147], v238 offset:224
	v_add_u32_e32 v243, 256, v240
	v_ashrrev_i32_e32 v241, 3, v243
	v_and_b32_e32 v241, -16, v241
	v_lshl_add_u32 v241, v243, 1, v241
	v_add_u32_e32 v243, 320, v240
	v_ashrrev_i32_e32 v242, 3, v243
	v_and_b32_e32 v242, -16, v242
	v_lshl_add_u32 v242, v243, 1, v242
	s_waitcnt lgkmcnt(9)
	v_mfma_f32_32x32x16_bf16 v[2:17], v[76:79], v[92:95], v[2:17]
	v_mfma_f32_32x32x16_bf16 v[18:33], v[76:79], v[96:99], v[18:33]
	ds_read_b128 v[76:79], v241
	ds_read_b128 v[92:95], v238 offset:256
	v_mfma_f32_32x32x16_bf16 v[2:17], v[80:83], v[96:99], v[2:17]
	v_mfma_f32_32x32x16_bf16 v[18:33], v[80:83], v[100:103], v[18:33]
	ds_read_b128 v[80:83], v241 offset:16
	ds_read_b128 v[96:99], v239 offset:256
	v_mfma_f32_32x32x16_bf16 v[2:17], v[84:87], v[100:103], v[2:17]
	v_mfma_f32_32x32x16_bf16 v[18:33], v[84:87], v[104:107], v[18:33]
	ds_read_b128 v[84:87], v241 offset:32
	ds_read_b128 v[100:103], v238 offset:272
	v_mfma_f32_32x32x16_bf16 v[2:17], v[88:91], v[104:107], v[2:17]
	v_mfma_f32_32x32x16_bf16 v[18:33], v[88:91], v[108:111], v[18:33]
	ds_read_b128 v[88:91], v241 offset:48
	ds_read_b128 v[104:107], v239 offset:272
	ds_read_b128 v[108:111], v238 offset:288
	s_waitcnt lgkmcnt(9)
	v_mfma_f32_32x32x16_bf16 v[2:17], v[112:115], v[128:131], v[2:17]
	v_mfma_f32_32x32x16_bf16 v[18:33], v[112:115], v[132:135], v[18:33]
	ds_read_b128 v[112:115], v242
	ds_read_b128 v[128:131], v238 offset:320
	v_mfma_f32_32x32x16_bf16 v[2:17], v[116:119], v[132:135], v[2:17]
	v_mfma_f32_32x32x16_bf16 v[18:33], v[116:119], v[136:139], v[18:33]
	ds_read_b128 v[116:119], v242 offset:16
	ds_read_b128 v[132:135], v239 offset:320
	v_mfma_f32_32x32x16_bf16 v[2:17], v[120:123], v[136:139], v[2:17]
	v_mfma_f32_32x32x16_bf16 v[18:33], v[120:123], v[140:143], v[18:33]
	ds_read_b128 v[120:123], v242 offset:32
	ds_read_b128 v[136:139], v238 offset:336
	v_mfma_f32_32x32x16_bf16 v[2:17], v[124:127], v[140:143], v[2:17]
	v_mfma_f32_32x32x16_bf16 v[18:33], v[124:127], v[144:147], v[18:33]
	ds_read_b128 v[124:127], v242 offset:48
	ds_read_b128 v[140:143], v239 offset:336
	ds_read_b128 v[144:147], v238 offset:352
	s_waitcnt lgkmcnt(9)
	v_mfma_f32_32x32x16_bf16 v[2:17], v[76:79], v[92:95], v[2:17]
	v_mfma_f32_32x32x16_bf16 v[18:33], v[76:79], v[96:99], v[18:33]
	v_mfma_f32_32x32x16_bf16 v[2:17], v[80:83], v[96:99], v[2:17]
	v_mfma_f32_32x32x16_bf16 v[18:33], v[80:83], v[100:103], v[18:33]
	v_mfma_f32_32x32x16_bf16 v[2:17], v[84:87], v[100:103], v[2:17]
	v_mfma_f32_32x32x16_bf16 v[18:33], v[84:87], v[104:107], v[18:33]
	v_mfma_f32_32x32x16_bf16 v[2:17], v[88:91], v[104:107], v[2:17]
	v_mfma_f32_32x32x16_bf16 v[18:33], v[88:91], v[108:111], v[18:33]
	s_waitcnt lgkmcnt(0)
	s_addk_i32 s1, 0x180
	s_cmpk_eq_i32 s1, 0xf00
	v_mfma_f32_32x32x16_bf16 v[2:17], v[112:115], v[128:131], v[2:17]
	v_mfma_f32_32x32x16_bf16 v[18:33], v[112:115], v[132:135], v[18:33]
	v_mfma_f32_32x32x16_bf16 v[2:17], v[116:119], v[132:135], v[2:17]
	v_mfma_f32_32x32x16_bf16 v[18:33], v[116:119], v[136:139], v[18:33]
	v_mfma_f32_32x32x16_bf16 v[2:17], v[120:123], v[136:139], v[2:17]
	v_mfma_f32_32x32x16_bf16 v[18:33], v[120:123], v[140:143], v[18:33]
	v_mfma_f32_32x32x16_bf16 v[2:17], v[124:127], v[140:143], v[2:17]
	v_mfma_f32_32x32x16_bf16 v[18:33], v[124:127], v[144:147], v[18:33]
	s_nop 0
	s_nop 0
	s_nop 0
	s_nop 0
	s_nop 0
	s_nop 0
	s_nop 0
	s_nop 0
	s_nop 0
	s_nop 0
	s_nop 0
	s_nop 0
	s_nop 0
	s_nop 0
	s_nop 0
	s_cbranch_scc1 .LBB0_874
